# spatial gating: u tiles and bias words of the current unit touched during the MFMA section
# baseline (speedup 1.0000x reference)
.LBB11_1433:
	s_waitcnt lgkmcnt(0)
	s_waitcnt lgkmcnt(0)
	s_barrier
	ds_read_u16 v70, v175 offset:520
	ds_read_u16 v71, v175 offset:1040
	ds_read_u16 v74, v175 offset:1560
	ds_read_u16 v72, v175 offset:2080
	ds_read_u16 v75, v175 offset:2600
	ds_read_u16 v73, v175 offset:3120
	ds_read_u16 v76, v175 offset:3640
	ds_read_u16 v77, v175
	ds_read_u16 v78, v175 offset:32
	ds_read_u16 v79, v175 offset:552
	ds_read_u16 v80, v175 offset:1072
	ds_read_u16 v81, v175 offset:1592
	ds_read_u16 v82, v175 offset:2112
	ds_read_u16 v83, v175 offset:2632
	ds_read_u16 v84, v175 offset:3152
	ds_read_u16 v85, v175 offset:3672
	ds_read_b128 v[66:69], v193
	s_waitcnt lgkmcnt(10)
	v_perm_b32 v73, v76, v73, s85
	v_perm_b32 v72, v75, v72, s85
	v_perm_b32 v71, v74, v71, s85
	s_waitcnt lgkmcnt(9)
	v_perm_b32 v70, v70, v77, s85
	s_waitcnt lgkmcnt(1)
	v_perm_b32 v77, v85, v84, s85
	v_perm_b32 v76, v83, v82, s85
	v_perm_b32 v75, v81, v80, s85
	v_perm_b32 v74, v79, v78, s85
	ds_read_b128 v[98:101], v193 offset:21760
	s_waitcnt lgkmcnt(1)
	v_mfma_f32_16x16x32_bf16 v[126:129], v[70:73], v[66:69], 0
	ds_read_b128 v[82:85], v193 offset:13056
	ds_read_b128 v[90:93], v193 offset:17408
	s_and_b32 s16, s6, 0xffffff80
	v_mfma_f32_16x16x32_bf16 v[122:125], v[74:77], v[66:69], 0
	ds_read_b128 v[66:69], v193 offset:4352
	s_add_i32 s16, s16, s8
	s_mov_b64 s[100:101], 0x20000
	v_or_b32_e32 v232, s16, v172
	v_ashrrev_i32_e32 v233, 31, v232
	v_lshlrev_b64 v[232:233], 13, v[232:233]
	v_lshl_add_u64 v[232:233], v[160:161], 0, v[232:233]
	global_load_dword v231, v[232:233], off
	global_load_dword v231, v[232:233], off offset:32
	v_lshl_add_u64 v[232:233], v[232:233], 0, s[100:101]
	global_load_dword v231, v[232:233], off
	global_load_dword v231, v[232:233], off offset:32
	v_lshl_add_u64 v[232:233], v[232:233], 0, s[100:101]
	global_load_dword v231, v[232:233], off
	global_load_dword v231, v[232:233], off offset:32
	v_lshl_add_u64 v[232:233], v[232:233], 0, s[100:101]
	global_load_dword v231, v[232:233], off
	global_load_dword v231, v[232:233], off offset:32
	v_lshl_add_u64 v[232:233], v[232:233], 0, s[100:101]
	global_load_dword v231, v[232:233], off
	global_load_dword v231, v[232:233], off offset:32
	v_lshl_add_u64 v[232:233], v[232:233], 0, s[100:101]
	global_load_dword v231, v[232:233], off
	global_load_dword v231, v[232:233], off offset:32
	v_lshl_add_u64 v[232:233], v[232:233], 0, s[100:101]
	global_load_dword v231, v[232:233], off
	global_load_dword v231, v[232:233], off offset:32
	v_lshl_add_u64 v[232:233], v[232:233], 0, s[100:101]
	global_load_dword v231, v[232:233], off
	global_load_dword v231, v[232:233], off offset:32
	global_load_dword v231, v[156:157], off
	global_load_dword v231, v[156:157], off offset:128
	global_load_dword v231, v[156:157], off offset:256
	global_load_dword v231, v[156:157], off offset:384
	s_add_i32 s18, s18, 16
	s_waitcnt lgkmcnt(3)
	v_mfma_f32_16x16x32_bf16 v[166:169], v[70:73], v[98:101], 0
	s_andn2_b64 vcc, exec, s[14:15]
	s_mov_b32 s6, s19
	v_mfma_f32_16x16x32_bf16 v[194:197], v[74:77], v[98:101], 0
	ds_read_b128 v[98:101], v193 offset:26112
	s_waitcnt lgkmcnt(1)
	v_mfma_f32_16x16x32_bf16 v[118:121], v[70:73], v[66:69], 0
	v_mfma_f32_16x16x32_bf16 v[114:117], v[74:77], v[66:69], 0
	ds_read_b128 v[66:69], v193 offset:8704
	s_waitcnt lgkmcnt(1)
	v_mfma_f32_16x16x32_bf16 v[214:217], v[70:73], v[98:101], 0
	v_mfma_f32_16x16x32_bf16 v[218:221], v[74:77], v[98:101], 0
	ds_read_b128 v[98:101], v193 offset:30464
	s_waitcnt lgkmcnt(1)
	v_mfma_f32_16x16x32_bf16 v[78:81], v[70:73], v[66:69], 0
	v_mfma_f32_16x16x32_bf16 v[66:69], v[74:77], v[66:69], 0
	v_mfma_f32_16x16x32_bf16 v[86:89], v[70:73], v[82:85], 0
	v_mfma_f32_16x16x32_bf16 v[82:85], v[74:77], v[82:85], 0
	v_mfma_f32_16x16x32_bf16 v[94:97], v[70:73], v[90:93], 0
	v_mfma_f32_16x16x32_bf16 v[90:93], v[74:77], v[90:93], 0
	s_waitcnt lgkmcnt(0)
	v_mfma_f32_16x16x32_bf16 v[70:73], v[70:73], v[98:101], 0
	v_mfma_f32_16x16x32_bf16 v[74:77], v[74:77], v[98:101], 0
	ds_read_u16 v102, v175 offset:16640
	ds_read_u16 v103, v175 offset:17160
	ds_read_u16 v104, v175 offset:17680
	ds_read_u16 v105, v175 offset:18200
	ds_read_u16 v106, v175 offset:18720
	ds_read_u16 v107, v175 offset:19240
	ds_read_u16 v108, v175 offset:19760
	ds_read_u16 v109, v175 offset:20280
	ds_read_u16 v170, v175 offset:16672
	ds_read_u16 v171, v175 offset:17192
	ds_read_u16 v213, v175 offset:17712
	ds_read_u16 v226, v175 offset:18232
	ds_read_u16 v227, v175 offset:18752
	ds_read_u16 v228, v175 offset:19272
	ds_read_u16 v229, v175 offset:19792
	ds_read_u16 v230, v175 offset:20312
	ds_read_b128 v[98:101], v193 offset:8768
	s_waitcnt lgkmcnt(9)
	v_perm_b32 v225, v109, v108, s85
	v_perm_b32 v224, v107, v106, s85
	v_perm_b32 v223, v105, v104, s85
	v_perm_b32 v222, v103, v102, s85
	s_waitcnt lgkmcnt(0)
	s_nop 0
	v_mfma_f32_16x16x32_bf16 v[110:113], v[222:225], v[98:101], v[78:81]
	s_nop 2
	v_perm_b32 v81, v230, v229, s85
	v_perm_b32 v80, v228, v227, s85
	v_perm_b32 v79, v226, v213, s85
	v_perm_b32 v78, v171, v170, s85
	s_nop 1
	v_mfma_f32_16x16x32_bf16 v[106:109], v[78:81], v[98:101], v[66:69]
	s_nop 2
	ds_read_b128 v[66:69], v193 offset:13120
	s_waitcnt lgkmcnt(0)
	v_mfma_f32_16x16x32_bf16 v[102:105], v[222:225], v[66:69], v[86:89]
	s_nop 2
	ds_read_b128 v[86:89], v193 offset:21824
	v_mfma_f32_16x16x32_bf16 v[98:101], v[78:81], v[66:69], v[82:85]
	ds_read_b128 v[66:69], v193 offset:17472
	s_waitcnt lgkmcnt(1)
	v_mfma_f32_16x16x32_bf16 v[166:169], v[222:225], v[86:89], v[166:169]
	v_mfma_f32_16x16x32_bf16 v[194:197], v[78:81], v[86:89], v[194:197]
	ds_read_b128 v[86:89], v193 offset:26176
	s_waitcnt lgkmcnt(0)
	v_mfma_f32_16x16x32_bf16 v[214:217], v[222:225], v[86:89], v[214:217]
	v_mfma_f32_16x16x32_bf16 v[218:221], v[78:81], v[86:89], v[218:221]
	ds_read_b128 v[86:89], v193 offset:30528
	v_mfma_f32_16x16x32_bf16 v[82:85], v[222:225], v[66:69], v[94:97]
	v_mfma_f32_16x16x32_bf16 v[66:69], v[78:81], v[66:69], v[90:93]
	s_waitcnt lgkmcnt(0)
	v_mfma_f32_16x16x32_bf16 v[70:73], v[222:225], v[86:89], v[70:73]
	v_mfma_f32_16x16x32_bf16 v[74:77], v[78:81], v[86:89], v[74:77]
	ds_read_u16 v86, v175 offset:33280
	ds_read_u16 v87, v175 offset:33800
	ds_read_u16 v88, v175 offset:34320
	ds_read_u16 v89, v175 offset:34840
	ds_read_u16 v90, v175 offset:35360
	ds_read_u16 v91, v175 offset:35880
	ds_read_u16 v92, v175 offset:36400
	ds_read_u16 v93, v175 offset:36920
	ds_read_u16 v170, v175 offset:33312
	ds_read_u16 v171, v175 offset:33832
	ds_read_u16 v213, v175 offset:34352
	ds_read_u16 v226, v175 offset:34872
	ds_read_u16 v227, v175 offset:35392
	ds_read_u16 v228, v175 offset:35912
	ds_read_u16 v229, v175 offset:36432
	ds_read_u16 v230, v175 offset:36952
	ds_read_b128 v[78:81], v193 offset:17536
	s_waitcnt lgkmcnt(9)
	v_perm_b32 v225, v93, v92, s85
	s_waitcnt lgkmcnt(3)
	v_perm_b32 v228, v228, v227, s85
	v_perm_b32 v227, v226, v213, s85
	s_waitcnt lgkmcnt(1)
	v_perm_b32 v229, v230, v229, s85
	v_perm_b32 v226, v171, v170, s85
	v_perm_b32 v224, v91, v90, s85
	v_perm_b32 v223, v89, v88, s85
	v_perm_b32 v222, v87, v86, s85
	s_waitcnt lgkmcnt(0)
	v_mfma_f32_16x16x32_bf16 v[90:93], v[226:229], v[78:81], v[66:69]
	s_nop 2
	ds_read_b128 v[66:69], v193 offset:21888
	v_mfma_f32_16x16x32_bf16 v[94:97], v[222:225], v[78:81], v[82:85]
	s_waitcnt lgkmcnt(0)
	v_mfma_f32_16x16x32_bf16 v[86:89], v[222:225], v[66:69], v[166:169]
	v_mfma_f32_16x16x32_bf16 v[82:85], v[226:229], v[66:69], v[194:197]
	ds_read_b128 v[66:69], v193 offset:26240
	s_nop 0
	ds_read_b128 v[166:169], v193 offset:30592
	s_waitcnt lgkmcnt(1)
	v_mfma_f32_16x16x32_bf16 v[78:81], v[222:225], v[66:69], v[214:217]
	v_mfma_f32_16x16x32_bf16 v[66:69], v[226:229], v[66:69], v[218:221]
	s_waitcnt lgkmcnt(0)
	v_mfma_f32_16x16x32_bf16 v[70:73], v[222:225], v[166:169], v[70:73]
	v_mfma_f32_16x16x32_bf16 v[166:169], v[226:229], v[166:169], v[74:77]
	ds_read_u16 v170, v175 offset:49920
	ds_read_u16 v171, v175 offset:50440
	ds_read_u16 v194, v175 offset:50960
	ds_read_u16 v195, v175 offset:51480
	ds_read_u16 v196, v175 offset:52000
	ds_read_u16 v213, v175 offset:52520
	ds_read_u16 v197, v175 offset:53040
	ds_read_u16 v214, v175 offset:53560
	ds_read_u16 v218, v175 offset:49952
	ds_read_u16 v219, v175 offset:50472
	ds_read_u16 v215, v175 offset:50992
	ds_read_u16 v220, v175 offset:51512
	ds_read_u16 v216, v175 offset:52032
	ds_read_u16 v221, v175 offset:52552
	ds_read_u16 v217, v175 offset:53072
	ds_read_u16 v222, v175 offset:53592
	ds_read_b128 v[74:77], v193 offset:26304
	s_waitcnt lgkmcnt(9)
	v_perm_b32 v197, v214, v197, s85
	v_perm_b32 v196, v213, v196, s85
	v_perm_b32 v195, v195, v194, s85
	v_perm_b32 v194, v171, v170, s85
	s_waitcnt lgkmcnt(1)
	v_perm_b32 v217, v222, v217, s85
	v_perm_b32 v216, v221, v216, s85
	v_perm_b32 v215, v220, v215, s85
	v_perm_b32 v214, v219, v218, s85
	s_waitcnt lgkmcnt(0)
	v_mfma_f32_16x16x32_bf16 v[78:81], v[194:197], v[74:77], v[78:81]
	v_mfma_f32_16x16x32_bf16 v[74:77], v[214:217], v[74:77], v[66:69]
	s_nop 2
	ds_read_b128 v[66:69], v193 offset:30656
	s_waitcnt lgkmcnt(0)
	v_mfma_f32_16x16x32_bf16 v[70:73], v[194:197], v[66:69], v[70:73]
	global_load_dword v194, v[154:155], off
	s_waitcnt vmcnt(0)
	v_add_f32_e32 v126, v126, v194
	v_mfma_f32_16x16x32_bf16 v[66:69], v[214:217], v[66:69], v[166:169]
	v_add_f32_e32 v127, v127, v194
	v_add_f32_e32 v128, v128, v194
	v_add_f32_e32 v129, v129, v194
	v_or_b32_e32 v166, s16, v172
	v_ashrrev_i32_e32 v167, 31, v166
	v_lshlrev_b64 v[170:171], 13, v[166:167]
	v_lshlrev_b64 v[168:169], 12, v[166:167]
	v_lshl_add_u64 v[166:167], v[160:161], 0, v[170:171]
	global_load_dwordx2 v[170:171], v[166:167], off
	v_add_f32_e32 v122, v122, v194
	v_add_f32_e32 v123, v123, v194
	v_add_f32_e32 v124, v124, v194
	v_add_f32_e32 v125, v125, v194
	s_waitcnt vmcnt(0)
	v_lshlrev_b32_e32 v195, 16, v170
	v_and_b32_e32 v170, 0xffff0000, v170
	v_mul_f32_e32 v126, v126, v195
	v_mul_f32_e32 v127, v127, v170
	v_cvt_pk_bf16_f32 v126, v126, v127
	v_lshlrev_b32_e32 v127, 16, v171
	v_mul_f32_e32 v127, v128, v127
	v_and_b32_e32 v128, 0xffff0000, v171
	v_mul_f32_e32 v128, v129, v128
	v_cvt_pk_bf16_f32 v127, v127, v128
	v_lshl_add_u64 v[128:129], v[162:163], 0, v[168:169]
	global_store_dwordx2 v[128:129], v[126:127], off
	global_load_dwordx2 v[126:127], v[166:167], off offset:32
	s_waitcnt vmcnt(0)
	v_lshlrev_b32_e32 v166, 16, v126
	v_and_b32_e32 v126, 0xffff0000, v126
	v_mul_f32_e32 v122, v122, v166
	v_mul_f32_e32 v123, v123, v126
	v_cvt_pk_bf16_f32 v122, v122, v123
	v_lshlrev_b32_e32 v123, 16, v127
	v_mul_f32_e32 v123, v124, v123
	v_and_b32_e32 v124, 0xffff0000, v127
	v_mul_f32_e32 v124, v125, v124
	v_cvt_pk_bf16_f32 v123, v123, v124
	global_store_dwordx2 v[128:129], v[122:123], off offset:32
	v_or_b32_e32 v122, s16, v176
	v_ashrrev_i32_e32 v123, 31, v122
	v_lshlrev_b64 v[124:125], 13, v[122:123]
	v_lshl_add_u64 v[124:125], v[160:161], 0, v[124:125]
	global_load_dword v128, v[156:157], off offset:64
	global_load_dwordx2 v[126:127], v[124:125], off
	v_lshlrev_b64 v[122:123], 12, v[122:123]
	s_waitcnt vmcnt(1)
	v_add_f32_e32 v118, v118, v128
	s_waitcnt vmcnt(0)
	v_lshlrev_b32_e32 v129, 16, v126
	v_and_b32_e32 v126, 0xffff0000, v126
	v_add_f32_e32 v119, v119, v128
	v_mul_f32_e32 v118, v118, v129
	v_mul_f32_e32 v119, v119, v126
	v_cvt_pk_bf16_f32 v118, v118, v119
	v_lshlrev_b32_e32 v119, 16, v127
	v_add_f32_e32 v120, v120, v128
	v_mul_f32_e32 v119, v120, v119
	v_and_b32_e32 v120, 0xffff0000, v127
	v_add_f32_e32 v121, v121, v128
	v_mul_f32_e32 v120, v121, v120
	v_cvt_pk_bf16_f32 v119, v119, v120
	v_lshl_add_u64 v[120:121], v[162:163], 0, v[122:123]
	global_store_dwordx2 v[120:121], v[118:119], off
	global_load_dwordx2 v[118:119], v[124:125], off offset:32
	v_add_f32_e32 v114, v114, v128
	v_add_f32_e32 v115, v115, v128
	v_add_f32_e32 v116, v116, v128
	v_add_f32_e32 v117, v117, v128
	s_waitcnt vmcnt(0)
	v_lshlrev_b32_e32 v122, 16, v118
	v_and_b32_e32 v118, 0xffff0000, v118
	v_mul_f32_e32 v114, v114, v122
	v_mul_f32_e32 v115, v115, v118
	v_cvt_pk_bf16_f32 v114, v114, v115
	v_lshlrev_b32_e32 v115, 16, v119
	v_mul_f32_e32 v115, v116, v115
	v_and_b32_e32 v116, 0xffff0000, v119
	v_mul_f32_e32 v116, v117, v116
	v_cvt_pk_bf16_f32 v115, v115, v116
	global_store_dwordx2 v[120:121], v[114:115], off offset:32
	v_or_b32_e32 v114, s16, v177
	v_ashrrev_i32_e32 v115, 31, v114
	v_lshlrev_b64 v[116:117], 13, v[114:115]
	v_lshl_add_u64 v[116:117], v[160:161], 0, v[116:117]
	global_load_dword v120, v[156:157], off offset:128
	global_load_dwordx2 v[118:119], v[116:117], off
	v_lshlrev_b64 v[114:115], 12, v[114:115]
	s_waitcnt vmcnt(1)
	v_add_f32_e32 v110, v110, v120
	s_waitcnt vmcnt(0)
	v_lshlrev_b32_e32 v121, 16, v118
	v_and_b32_e32 v118, 0xffff0000, v118
	v_add_f32_e32 v111, v111, v120
	v_mul_f32_e32 v110, v110, v121
	v_mul_f32_e32 v111, v111, v118
	v_cvt_pk_bf16_f32 v110, v110, v111
	v_lshlrev_b32_e32 v111, 16, v119
	v_add_f32_e32 v112, v112, v120
	v_mul_f32_e32 v111, v112, v111
	v_and_b32_e32 v112, 0xffff0000, v119
	v_add_f32_e32 v113, v113, v120
	v_mul_f32_e32 v112, v113, v112
	v_cvt_pk_bf16_f32 v111, v111, v112
	v_lshl_add_u64 v[112:113], v[162:163], 0, v[114:115]
	global_store_dwordx2 v[112:113], v[110:111], off
	global_load_dwordx2 v[110:111], v[116:117], off offset:32
	v_add_f32_e32 v106, v106, v120
	v_add_f32_e32 v107, v107, v120
	v_add_f32_e32 v108, v108, v120
	v_add_f32_e32 v109, v109, v120
	s_waitcnt vmcnt(0)
	v_lshlrev_b32_e32 v114, 16, v110
	v_and_b32_e32 v110, 0xffff0000, v110
	v_mul_f32_e32 v106, v106, v114
	v_mul_f32_e32 v107, v107, v110
	v_cvt_pk_bf16_f32 v106, v106, v107
	v_lshlrev_b32_e32 v107, 16, v111
	v_mul_f32_e32 v107, v108, v107
	v_and_b32_e32 v108, 0xffff0000, v111
	v_mul_f32_e32 v108, v109, v108
	v_cvt_pk_bf16_f32 v107, v107, v108
	global_store_dwordx2 v[112:113], v[106:107], off offset:32
	v_or_b32_e32 v106, s16, v178
	v_ashrrev_i32_e32 v107, 31, v106
	v_lshlrev_b64 v[108:109], 13, v[106:107]
	v_lshl_add_u64 v[108:109], v[160:161], 0, v[108:109]
	global_load_dword v112, v[156:157], off offset:192
	global_load_dwordx2 v[110:111], v[108:109], off
	v_lshlrev_b64 v[106:107], 12, v[106:107]
	s_waitcnt vmcnt(1)
	v_add_f32_e32 v102, v102, v112
	s_waitcnt vmcnt(0)
	v_lshlrev_b32_e32 v113, 16, v110
	v_and_b32_e32 v110, 0xffff0000, v110
	v_add_f32_e32 v103, v103, v112
	v_mul_f32_e32 v102, v102, v113
	v_mul_f32_e32 v103, v103, v110
	v_cvt_pk_bf16_f32 v102, v102, v103
	v_lshlrev_b32_e32 v103, 16, v111
	v_add_f32_e32 v104, v104, v112
	v_mul_f32_e32 v103, v104, v103
	v_and_b32_e32 v104, 0xffff0000, v111
	v_add_f32_e32 v105, v105, v112
	v_mul_f32_e32 v104, v105, v104
	v_cvt_pk_bf16_f32 v103, v103, v104
	v_lshl_add_u64 v[104:105], v[162:163], 0, v[106:107]
	global_store_dwordx2 v[104:105], v[102:103], off
	global_load_dwordx2 v[102:103], v[108:109], off offset:32
	v_add_f32_e32 v98, v98, v112
	v_add_f32_e32 v99, v99, v112
	v_add_f32_e32 v100, v100, v112
	v_add_f32_e32 v101, v101, v112
	s_waitcnt vmcnt(0)
	v_lshlrev_b32_e32 v106, 16, v102
	v_and_b32_e32 v102, 0xffff0000, v102
	v_mul_f32_e32 v98, v98, v106
	v_mul_f32_e32 v99, v99, v102
	v_cvt_pk_bf16_f32 v98, v98, v99
	v_lshlrev_b32_e32 v99, 16, v103
	v_mul_f32_e32 v99, v100, v99
	v_and_b32_e32 v100, 0xffff0000, v103
	v_mul_f32_e32 v100, v101, v100
	v_cvt_pk_bf16_f32 v99, v99, v100
	global_store_dwordx2 v[104:105], v[98:99], off offset:32
	v_or_b32_e32 v98, s16, v179
	v_ashrrev_i32_e32 v99, 31, v98
	v_lshlrev_b64 v[100:101], 13, v[98:99]
	v_lshl_add_u64 v[100:101], v[160:161], 0, v[100:101]
	global_load_dword v104, v[156:157], off offset:256
	global_load_dwordx2 v[102:103], v[100:101], off
	v_lshlrev_b64 v[98:99], 12, v[98:99]
	s_waitcnt vmcnt(1)
	v_add_f32_e32 v94, v94, v104
	s_waitcnt vmcnt(0)
	v_lshlrev_b32_e32 v105, 16, v102
	v_and_b32_e32 v102, 0xffff0000, v102
	v_add_f32_e32 v95, v95, v104
	v_mul_f32_e32 v94, v94, v105
	v_mul_f32_e32 v95, v95, v102
	v_cvt_pk_bf16_f32 v94, v94, v95
	v_lshlrev_b32_e32 v95, 16, v103
	v_add_f32_e32 v96, v96, v104
	v_mul_f32_e32 v95, v96, v95
	v_and_b32_e32 v96, 0xffff0000, v103
	v_add_f32_e32 v97, v97, v104
	v_mul_f32_e32 v96, v97, v96
	v_cvt_pk_bf16_f32 v95, v95, v96
	v_lshl_add_u64 v[96:97], v[162:163], 0, v[98:99]
	global_store_dwordx2 v[96:97], v[94:95], off
	global_load_dwordx2 v[94:95], v[100:101], off offset:32
	v_add_f32_e32 v90, v90, v104
	v_add_f32_e32 v91, v91, v104
	v_add_f32_e32 v92, v92, v104
	v_add_f32_e32 v93, v93, v104
	s_waitcnt vmcnt(0)
	v_lshlrev_b32_e32 v98, 16, v94
	v_and_b32_e32 v94, 0xffff0000, v94
	v_mul_f32_e32 v90, v90, v98
	v_mul_f32_e32 v91, v91, v94
	v_cvt_pk_bf16_f32 v90, v90, v91
	v_lshlrev_b32_e32 v91, 16, v95
	v_mul_f32_e32 v91, v92, v91
	v_and_b32_e32 v92, 0xffff0000, v95
	v_mul_f32_e32 v92, v93, v92
	v_cvt_pk_bf16_f32 v91, v91, v92
	global_store_dwordx2 v[96:97], v[90:91], off offset:32
	v_or_b32_e32 v90, s16, v180
	v_ashrrev_i32_e32 v91, 31, v90
	v_lshlrev_b64 v[92:93], 13, v[90:91]
	v_lshl_add_u64 v[92:93], v[160:161], 0, v[92:93]
	global_load_dword v96, v[156:157], off offset:320
	global_load_dwordx2 v[94:95], v[92:93], off
	v_lshlrev_b64 v[90:91], 12, v[90:91]
	s_waitcnt vmcnt(1)
	v_add_f32_e32 v86, v86, v96
	s_waitcnt vmcnt(0)
	v_lshlrev_b32_e32 v97, 16, v94
	v_and_b32_e32 v94, 0xffff0000, v94
	v_add_f32_e32 v87, v87, v96
	v_mul_f32_e32 v86, v86, v97
	v_mul_f32_e32 v87, v87, v94
	v_cvt_pk_bf16_f32 v86, v86, v87
	v_lshlrev_b32_e32 v87, 16, v95
	v_add_f32_e32 v88, v88, v96
	v_mul_f32_e32 v87, v88, v87
	v_and_b32_e32 v88, 0xffff0000, v95
	v_add_f32_e32 v89, v89, v96
	v_mul_f32_e32 v88, v89, v88
	v_cvt_pk_bf16_f32 v87, v87, v88
	v_lshl_add_u64 v[88:89], v[162:163], 0, v[90:91]
	global_store_dwordx2 v[88:89], v[86:87], off
	global_load_dwordx2 v[86:87], v[92:93], off offset:32
	v_add_f32_e32 v82, v82, v96
	v_add_f32_e32 v83, v83, v96
	v_add_f32_e32 v84, v84, v96
	v_add_f32_e32 v85, v85, v96
	s_waitcnt vmcnt(0)
	v_lshlrev_b32_e32 v90, 16, v86
	v_and_b32_e32 v86, 0xffff0000, v86
	v_mul_f32_e32 v82, v82, v90
	v_mul_f32_e32 v83, v83, v86
	v_cvt_pk_bf16_f32 v82, v82, v83
	v_lshlrev_b32_e32 v83, 16, v87
	v_mul_f32_e32 v83, v84, v83
	v_and_b32_e32 v84, 0xffff0000, v87
	v_mul_f32_e32 v84, v85, v84
	v_cvt_pk_bf16_f32 v83, v83, v84
	global_store_dwordx2 v[88:89], v[82:83], off offset:32
	v_or_b32_e32 v82, s16, v181
	v_ashrrev_i32_e32 v83, 31, v82
	v_lshlrev_b64 v[84:85], 13, v[82:83]
	v_lshl_add_u64 v[84:85], v[160:161], 0, v[84:85]
	global_load_dword v88, v[156:157], off offset:384
	global_load_dwordx2 v[86:87], v[84:85], off
	v_lshlrev_b64 v[82:83], 12, v[82:83]
	s_waitcnt vmcnt(1)
	v_add_f32_e32 v78, v78, v88
	s_waitcnt vmcnt(0)
	v_lshlrev_b32_e32 v89, 16, v86
	v_and_b32_e32 v86, 0xffff0000, v86
	v_add_f32_e32 v79, v79, v88
	v_mul_f32_e32 v78, v78, v89
	v_mul_f32_e32 v79, v79, v86
	v_cvt_pk_bf16_f32 v78, v78, v79
	v_lshlrev_b32_e32 v79, 16, v87
	v_add_f32_e32 v80, v80, v88
	v_mul_f32_e32 v79, v80, v79
	v_and_b32_e32 v80, 0xffff0000, v87
	v_add_f32_e32 v81, v81, v88
	v_mul_f32_e32 v80, v81, v80
	v_cvt_pk_bf16_f32 v79, v79, v80
	v_lshl_add_u64 v[80:81], v[162:163], 0, v[82:83]
	global_store_dwordx2 v[80:81], v[78:79], off
	global_load_dwordx2 v[78:79], v[84:85], off offset:32
	v_add_f32_e32 v74, v74, v88
	v_add_f32_e32 v75, v75, v88
	v_add_f32_e32 v76, v76, v88
	v_add_f32_e32 v77, v77, v88
	s_waitcnt vmcnt(0)
	v_lshlrev_b32_e32 v82, 16, v78
	v_and_b32_e32 v78, 0xffff0000, v78
	v_mul_f32_e32 v74, v74, v82
	v_mul_f32_e32 v75, v75, v78
	v_cvt_pk_bf16_f32 v74, v74, v75
	v_lshlrev_b32_e32 v75, 16, v79
	v_mul_f32_e32 v75, v76, v75
	v_and_b32_e32 v76, 0xffff0000, v79
	v_mul_f32_e32 v76, v77, v76
	v_cvt_pk_bf16_f32 v75, v75, v76
	global_store_dwordx2 v[80:81], v[74:75], off offset:32
	v_or_b32_e32 v74, s16, v174
	v_ashrrev_i32_e32 v75, 31, v74
	v_lshlrev_b64 v[76:77], 13, v[74:75]
	v_lshl_add_u64 v[76:77], v[160:161], 0, v[76:77]
	global_load_dword v80, v[156:157], off offset:448
	global_load_dwordx2 v[78:79], v[76:77], off
	v_lshlrev_b64 v[74:75], 12, v[74:75]
	s_waitcnt vmcnt(1)
	v_add_f32_e32 v70, v70, v80
	s_waitcnt vmcnt(0)
	v_lshlrev_b32_e32 v81, 16, v78
	v_and_b32_e32 v78, 0xffff0000, v78
	v_add_f32_e32 v71, v71, v80
	v_mul_f32_e32 v70, v70, v81
	v_mul_f32_e32 v71, v71, v78
	v_cvt_pk_bf16_f32 v70, v70, v71
	v_lshlrev_b32_e32 v71, 16, v79
	v_add_f32_e32 v72, v72, v80
	v_mul_f32_e32 v71, v72, v71
	v_and_b32_e32 v72, 0xffff0000, v79
	v_add_f32_e32 v73, v73, v80
	v_mul_f32_e32 v72, v73, v72
	v_cvt_pk_bf16_f32 v71, v71, v72
	v_lshl_add_u64 v[72:73], v[162:163], 0, v[74:75]
	global_store_dwordx2 v[72:73], v[70:71], off
	global_load_dwordx2 v[70:71], v[76:77], off offset:32
	v_add_f32_e32 v66, v66, v80
	v_add_f32_e32 v67, v67, v80
	v_add_f32_e32 v68, v68, v80
	v_add_f32_e32 v69, v69, v80
	s_waitcnt vmcnt(0)
	v_lshlrev_b32_e32 v74, 16, v70
	v_and_b32_e32 v70, 0xffff0000, v70
	v_mul_f32_e32 v66, v66, v74
	v_mul_f32_e32 v67, v67, v70
	v_cvt_pk_bf16_f32 v66, v66, v67
	v_lshlrev_b32_e32 v67, 16, v71
	v_mul_f32_e32 v67, v68, v67
	v_and_b32_e32 v68, 0xffff0000, v71
	v_mul_f32_e32 v68, v69, v68
	v_cvt_pk_bf16_f32 v67, v67, v68
	global_store_dwordx2 v[72:73], v[66:67], off offset:32
	s_cbranch_vccz .LBB11_1438

	.amdhsa_kernel _ZN2mk8mega_fwdENS_6ParamsE
		.amdhsa_group_segment_fixed_size 0
		.amdhsa_private_segment_fixed_size 0
		.amdhsa_kernarg_size 592
		.amdhsa_user_sgpr_count 2
		.amdhsa_user_sgpr_dispatch_ptr 0
		.amdhsa_user_sgpr_queue_ptr 0
		.amdhsa_user_sgpr_kernarg_segment_ptr 1
		.amdhsa_user_sgpr_dispatch_id 0
		.amdhsa_user_sgpr_kernarg_preload_length 0
		.amdhsa_user_sgpr_kernarg_preload_offset 0
		.amdhsa_user_sgpr_private_segment_size 0
		.amdhsa_uses_dynamic_stack 0
		.amdhsa_enable_private_segment 0
		.amdhsa_system_sgpr_workgroup_id_x 1
		.amdhsa_system_sgpr_workgroup_id_y 0
		.amdhsa_system_sgpr_workgroup_id_z 0
		.amdhsa_system_sgpr_workgroup_info 0
		.amdhsa_system_vgpr_workitem_id 0
		.amdhsa_next_free_vgpr 256
		.amdhsa_next_free_sgpr 102
		.amdhsa_accum_offset 256
		.amdhsa_reserve_vcc 1
		.amdhsa_float_round_mode_32 0
		.amdhsa_float_round_mode_16_64 0
		.amdhsa_float_denorm_mode_32 3
		.amdhsa_float_denorm_mode_16_64 3
		.amdhsa_dx10_clamp 1
		.amdhsa_ieee_mode 1
		.amdhsa_fp16_overflow 0
		.amdhsa_tg_split 0
		.amdhsa_exception_fp_ieee_invalid_op 0
		.amdhsa_exception_fp_denorm_src 0
		.amdhsa_exception_fp_ieee_div_zero 0
		.amdhsa_exception_fp_ieee_overflow 0
		.amdhsa_exception_fp_ieee_underflow 0
		.amdhsa_exception_fp_ieee_inexact 0
		.amdhsa_exception_int_div_zero 0
	.end_amdhsa_kernel

.Lfunc_end11:
	.size	_ZN2mk8mega_fwdENS_6ParamsE, .Lfunc_end11-_ZN2mk8mega_fwdENS_6ParamsE
	.set _ZN2mk8mega_fwdENS_6ParamsE.num_vgpr, 256
	.set _ZN2mk8mega_fwdENS_6ParamsE.num_agpr, 0
	.set _ZN2mk8mega_fwdENS_6ParamsE.numbered_sgpr, 102
	.set _ZN2mk8mega_fwdENS_6ParamsE.num_named_barrier, 0
	.set _ZN2mk8mega_fwdENS_6ParamsE.private_seg_size, 0
	.set _ZN2mk8mega_fwdENS_6ParamsE.uses_vcc, 1
	.set _ZN2mk8mega_fwdENS_6ParamsE.uses_flat_scratch, 0
	.set _ZN2mk8mega_fwdENS_6ParamsE.has_dyn_sized_stack, 0
	.set _ZN2mk8mega_fwdENS_6ParamsE.has_recursion, 0
	.set _ZN2mk8mega_fwdENS_6ParamsE.has_indirect_call, 0

amdhsa.kernels:
  - .agpr_count:     0
    .args:
      - .offset:         0
        .size:           128
        .value_kind:     by_value
    .group_segment_fixed_size: 8704
    .kernarg_segment_align: 8
    .kernarg_segment_size: 128
    .language:       OpenCL C
    .language_version:
      - 2
      - 0
    .max_flat_workgroup_size: 256
    .name:           _ZN2nv6k_gemmENS_5GemmPE
    .private_segment_fixed_size: 0
    .sgpr_count:     53
    .sgpr_spill_count: 0
    .symbol:         _ZN2nv6k_gemmENS_5GemmPE.kd
    .uniform_work_group_size: 1
    .uses_dynamic_stack: false
    .vgpr_count:     88
    .vgpr_spill_count: 0
    .wavefront_size: 64
  - .agpr_count:     0
    .args:
      - .address_space:  global
        .offset:         0
        .size:           8
        .value_kind:     global_buffer
      - .address_space:  global
        .offset:         8
        .size:           8
        .value_kind:     global_buffer
      - .address_space:  global
        .offset:         16
        .size:           8
        .value_kind:     global_buffer
      - .offset:         24
        .size:           4
        .value_kind:     by_value
    .group_segment_fixed_size: 0
    .kernarg_segment_align: 8
    .kernarg_segment_size: 28
    .language:       OpenCL C
    .language_version:
      - 2
      - 0
    .max_flat_workgroup_size: 256
    .name:           _ZN2nv9k_rmsnormEPKfS1_Pfi
    .private_segment_fixed_size: 0
    .sgpr_count:     14
    .sgpr_spill_count: 0
    .symbol:         _ZN2nv9k_rmsnormEPKfS1_Pfi.kd
    .uniform_work_group_size: 1
    .uses_dynamic_stack: false
    .vgpr_count:     31
    .vgpr_spill_count: 0
    .wavefront_size: 64
  - .agpr_count:     0
    .args:
      - .address_space:  global
        .offset:         0
        .size:           8
        .value_kind:     global_buffer
      - .address_space:  global
        .offset:         8
        .size:           8
        .value_kind:     global_buffer
      - .offset:         16
        .size:           8
        .value_kind:     by_value
      - .offset:         24
        .size:           4
        .value_kind:     hidden_block_count_x
      - .offset:         28
        .size:           4
        .value_kind:     hidden_block_count_y
      - .offset:         32
        .size:           4
        .value_kind:     hidden_block_count_z
      - .offset:         36
        .size:           2
        .value_kind:     hidden_group_size_x
      - .offset:         38
        .size:           2
        .value_kind:     hidden_group_size_y
      - .offset:         40
        .size:           2
        .value_kind:     hidden_group_size_z
      - .offset:         42
        .size:           2
        .value_kind:     hidden_remainder_x
      - .offset:         44
        .size:           2
        .value_kind:     hidden_remainder_y
      - .offset:         46
        .size:           2
        .value_kind:     hidden_remainder_z
      - .offset:         64
        .size:           8
        .value_kind:     hidden_global_offset_x
      - .offset:         72
        .size:           8
        .value_kind:     hidden_global_offset_y
      - .offset:         80
        .size:           8
        .value_kind:     hidden_global_offset_z
      - .offset:         88
        .size:           2
        .value_kind:     hidden_grid_dims
    .group_segment_fixed_size: 0
    .kernarg_segment_align: 8
    .kernarg_segment_size: 280
    .language:       OpenCL C
    .language_version:
      - 2
      - 0
    .max_flat_workgroup_size: 1024
    .name:           _ZN2nv6k_copyEPKfPfm
    .private_segment_fixed_size: 0
    .sgpr_count:     18
    .sgpr_spill_count: 0
    .symbol:         _ZN2nv6k_copyEPKfPfm.kd
    .uniform_work_group_size: 1
    .uses_dynamic_stack: false
    .vgpr_count:     7
    .vgpr_spill_count: 0
    .wavefront_size: 64
  - .agpr_count:     0
    .args:
      - .address_space:  global
        .offset:         0
        .size:           8
        .value_kind:     global_buffer
      - .address_space:  global
        .offset:         8
        .size:           8
        .value_kind:     global_buffer
      - .offset:         16
        .size:           8
        .value_kind:     by_value
      - .offset:         24
        .size:           4
        .value_kind:     hidden_block_count_x
      - .offset:         28
        .size:           4
        .value_kind:     hidden_block_count_y
      - .offset:         32
        .size:           4
        .value_kind:     hidden_block_count_z
      - .offset:         36
        .size:           2
        .value_kind:     hidden_group_size_x
      - .offset:         38
        .size:           2
        .value_kind:     hidden_group_size_y
      - .offset:         40
        .size:           2
        .value_kind:     hidden_group_size_z
      - .offset:         42
        .size:           2
        .value_kind:     hidden_remainder_x
      - .offset:         44
        .size:           2
        .value_kind:     hidden_remainder_y
      - .offset:         46
        .size:           2
        .value_kind:     hidden_remainder_z
      - .offset:         64
        .size:           8
        .value_kind:     hidden_global_offset_x
      - .offset:         72
        .size:           8
        .value_kind:     hidden_global_offset_y
      - .offset:         80
        .size:           8
        .value_kind:     hidden_global_offset_z
      - .offset:         88
        .size:           2
        .value_kind:     hidden_grid_dims
    .group_segment_fixed_size: 0
    .kernarg_segment_align: 8
    .kernarg_segment_size: 280
    .language:       OpenCL C
    .language_version:
      - 2
      - 0
    .max_flat_workgroup_size: 1024
    .name:           _ZN2nv8k_swigluEPfPKfm
    .private_segment_fixed_size: 0
    .sgpr_count:     24
    .sgpr_spill_count: 0
    .symbol:         _ZN2nv8k_swigluEPfPKfm.kd
    .uniform_work_group_size: 1
    .uses_dynamic_stack: false
    .vgpr_count:     15
    .vgpr_spill_count: 0
    .wavefront_size: 64
  - .agpr_count:     0
    .args:
      - .address_space:  global
        .offset:         0
        .size:           8
        .value_kind:     global_buffer
      - .offset:         8
        .size:           8
        .value_kind:     by_value
      - .offset:         16
        .size:           4
        .value_kind:     hidden_block_count_x
      - .offset:         20
        .size:           4
        .value_kind:     hidden_block_count_y
      - .offset:         24
        .size:           4
        .value_kind:     hidden_block_count_z
      - .offset:         28
        .size:           2
        .value_kind:     hidden_group_size_x
      - .offset:         30
        .size:           2
        .value_kind:     hidden_group_size_y
      - .offset:         32
        .size:           2
        .value_kind:     hidden_group_size_z
      - .offset:         34
        .size:           2
        .value_kind:     hidden_remainder_x
      - .offset:         36
        .size:           2
        .value_kind:     hidden_remainder_y
      - .offset:         38
        .size:           2
        .value_kind:     hidden_remainder_z
      - .offset:         56
        .size:           8
        .value_kind:     hidden_global_offset_x
      - .offset:         64
        .size:           8
        .value_kind:     hidden_global_offset_y
      - .offset:         72
        .size:           8
        .value_kind:     hidden_global_offset_z
      - .offset:         80
        .size:           2
        .value_kind:     hidden_grid_dims
    .group_segment_fixed_size: 0
    .kernarg_segment_align: 8
    .kernarg_segment_size: 272
    .language:       OpenCL C
    .language_version:
      - 2
      - 0
    .max_flat_workgroup_size: 1024
    .name:           _ZN2nv6k_geluEPfm
    .private_segment_fixed_size: 0
    .sgpr_count:     24
    .sgpr_spill_count: 0
    .symbol:         _ZN2nv6k_geluEPfm.kd
    .uniform_work_group_size: 1
    .uses_dynamic_stack: false
    .vgpr_count:     12
    .vgpr_spill_count: 0
    .wavefront_size: 64
  - .agpr_count:     0
    .args:
      - .address_space:  global
        .offset:         0
        .size:           8
        .value_kind:     global_buffer
      - .address_space:  global
        .offset:         8
        .size:           8
        .value_kind:     global_buffer
      - .address_space:  global
        .offset:         16
        .size:           8
        .value_kind:     global_buffer
      - .address_space:  global
        .offset:         24
        .size:           8
        .value_kind:     global_buffer
      - .offset:         32
        .size:           4
        .value_kind:     by_value
    .group_segment_fixed_size: 0
    .kernarg_segment_align: 8
    .kernarg_segment_size: 36
    .language:       OpenCL C
    .language_version:
      - 2
      - 0
    .max_flat_workgroup_size: 256
    .name:           _ZN2nv13k_layernorm_vEPKfS1_S1_Pfi
    .private_segment_fixed_size: 0
    .sgpr_count:     18
    .sgpr_spill_count: 0
    .symbol:         _ZN2nv13k_layernorm_vEPKfS1_S1_Pfi.kd
    .uniform_work_group_size: 1
    .uses_dynamic_stack: false
    .vgpr_count:     65
    .vgpr_spill_count: 0
    .wavefront_size: 64
  - .agpr_count:     0
    .args:
      - .address_space:  global
        .offset:         0
        .size:           8
        .value_kind:     global_buffer
      - .address_space:  global
        .offset:         8
        .size:           8
        .value_kind:     global_buffer
      - .address_space:  global
        .offset:         16
        .size:           8
        .value_kind:     global_buffer
      - .address_space:  global
        .offset:         24
        .size:           8
        .value_kind:     global_buffer
      - .address_space:  global
        .offset:         32
        .size:           8
        .value_kind:     global_buffer
    .group_segment_fixed_size: 0
    .kernarg_segment_align: 8
    .kernarg_segment_size: 40
    .language:       OpenCL C
    .language_version:
      - 2
      - 0
    .max_flat_workgroup_size: 256
    .name:           _ZN2nv5k_mixEPKfS1_S1_S1_Pf
    .private_segment_fixed_size: 0
    .sgpr_count:     22
    .sgpr_spill_count: 0
    .symbol:         _ZN2nv5k_mixEPKfS1_S1_S1_Pf.kd
    .uniform_work_group_size: 1
    .uses_dynamic_stack: false
    .vgpr_count:     10
    .vgpr_spill_count: 0
    .wavefront_size: 64
  - .agpr_count:     0
    .args:
      - .address_space:  global
        .offset:         0
        .size:           8
        .value_kind:     global_buffer
      - .address_space:  global
        .offset:         8
        .size:           8
        .value_kind:     global_buffer
      - .offset:         16
        .size:           4
        .value_kind:     by_value
      - .offset:         20
        .size:           4
        .value_kind:     by_value
      - .offset:         24
        .size:           4
        .value_kind:     by_value
      - .address_space:  global
        .offset:         32
        .size:           8
        .value_kind:     global_buffer
      - .address_space:  global
        .offset:         40
        .size:           8
        .value_kind:     global_buffer
      - .address_space:  global
        .offset:         48
        .size:           8
        .value_kind:     global_buffer
      - .address_space:  global
        .offset:         56
        .size:           8
        .value_kind:     global_buffer
      - .address_space:  global
        .offset:         64
        .size:           8
        .value_kind:     global_buffer
      - .address_space:  global
        .offset:         72
        .size:           8
        .value_kind:     global_buffer
      - .address_space:  global
        .offset:         80
        .size:           8
        .value_kind:     global_buffer
      - .address_space:  global
        .offset:         88
        .size:           8
        .value_kind:     global_buffer
      - .address_space:  global
        .offset:         96
        .size:           8
        .value_kind:     global_buffer
      - .address_space:  global
        .offset:         104
        .size:           8
        .value_kind:     global_buffer
      - .address_space:  global
        .offset:         112
        .size:           8
        .value_kind:     global_buffer
      - .address_space:  global
        .offset:         120
        .size:           8
        .value_kind:     global_buffer
    .group_segment_fixed_size: 576
    .kernarg_segment_align: 8
    .kernarg_segment_size: 128
    .language:       OpenCL C
    .language_version:
      - 2
      - 0
    .max_flat_workgroup_size: 64
    .name:           _ZN2nv5k_ssmEPKfPfiiiS1_S1_S2_S2_S1_S1_S1_S1_S1_S1_S1_S1_
    .private_segment_fixed_size: 0
    .sgpr_count:     36
    .sgpr_spill_count: 0
    .symbol:         _ZN2nv5k_ssmEPKfPfiiiS1_S1_S2_S2_S1_S1_S1_S1_S1_S1_S1_S1_.kd
    .uniform_work_group_size: 1
    .uses_dynamic_stack: false
    .vgpr_count:     127
    .vgpr_spill_count: 0
    .wavefront_size: 64
  - .agpr_count:     0
    .args:
      - .address_space:  global
        .offset:         0
        .size:           8
        .value_kind:     global_buffer
      - .address_space:  global
        .offset:         8
        .size:           8
        .value_kind:     global_buffer
      - .offset:         16
        .size:           8
        .value_kind:     by_value
      - .offset:         24
        .size:           4
        .value_kind:     hidden_block_count_x
      - .offset:         28
        .size:           4
        .value_kind:     hidden_block_count_y
      - .offset:         32
        .size:           4
        .value_kind:     hidden_block_count_z
      - .offset:         36
        .size:           2
        .value_kind:     hidden_group_size_x
      - .offset:         38
        .size:           2
        .value_kind:     hidden_group_size_y
      - .offset:         40
        .size:           2
        .value_kind:     hidden_group_size_z
      - .offset:         42
        .size:           2
        .value_kind:     hidden_remainder_x
      - .offset:         44
        .size:           2
        .value_kind:     hidden_remainder_y
      - .offset:         46
        .size:           2
        .value_kind:     hidden_remainder_z
      - .offset:         64
        .size:           8
        .value_kind:     hidden_global_offset_x
      - .offset:         72
        .size:           8
        .value_kind:     hidden_global_offset_y
      - .offset:         80
        .size:           8
        .value_kind:     hidden_global_offset_z
      - .offset:         88
        .size:           2
        .value_kind:     hidden_grid_dims
    .group_segment_fixed_size: 0
    .kernarg_segment_align: 8
    .kernarg_segment_size: 280
    .language:       OpenCL C
    .language_version:
      - 2
      - 0
    .max_flat_workgroup_size: 1024
    .name:           _ZN2nv9k_glu_addEPfPKfm
    .private_segment_fixed_size: 0
    .sgpr_count:     24
    .sgpr_spill_count: 0
    .symbol:         _ZN2nv9k_glu_addEPfPKfm.kd
    .uniform_work_group_size: 1
    .uses_dynamic_stack: false
    .vgpr_count:     16
    .vgpr_spill_count: 0
    .wavefront_size: 64
  - .agpr_count:     0
    .args:
      - .address_space:  global
        .offset:         0
        .size:           8
        .value_kind:     global_buffer
      - .offset:         8
        .size:           8
        .value_kind:     by_value
      - .offset:         16
        .size:           4
        .value_kind:     by_value
    .group_segment_fixed_size: 0
    .kernarg_segment_align: 8
    .kernarg_segment_size: 20
    .language:       OpenCL C
    .language_version:
      - 2
      - 0
    .max_flat_workgroup_size: 256
    .name:           _ZN2nv9k_softmaxEPfmf
    .private_segment_fixed_size: 0
    .sgpr_count:     14
    .sgpr_spill_count: 0
    .symbol:         _ZN2nv9k_softmaxEPfmf.kd
    .uniform_work_group_size: 1
    .uses_dynamic_stack: false
    .vgpr_count:     25
    .vgpr_spill_count: 0
    .wavefront_size: 64
  - .agpr_count:     0
    .args:
      - .address_space:  global
        .offset:         0
        .size:           8
        .value_kind:     global_buffer
      - .address_space:  global
        .offset:         8
        .size:           8
        .value_kind:     global_buffer
      - .offset:         16
        .size:           4
        .value_kind:     hidden_block_count_x
      - .offset:         20
        .size:           4
        .value_kind:     hidden_block_count_y
      - .offset:         24
        .size:           4
        .value_kind:     hidden_block_count_z
      - .offset:         28
        .size:           2
        .value_kind:     hidden_group_size_x
      - .offset:         30
        .size:           2
        .value_kind:     hidden_group_size_y
      - .offset:         32
        .size:           2
        .value_kind:     hidden_group_size_z
      - .offset:         34
        .size:           2
        .value_kind:     hidden_remainder_x
      - .offset:         36
        .size:           2
        .value_kind:     hidden_remainder_y
      - .offset:         38
        .size:           2
        .value_kind:     hidden_remainder_z
      - .offset:         56
        .size:           8
        .value_kind:     hidden_global_offset_x
      - .offset:         64
        .size:           8
        .value_kind:     hidden_global_offset_y
      - .offset:         72
        .size:           8
        .value_kind:     hidden_global_offset_z
      - .offset:         80
        .size:           2
        .value_kind:     hidden_grid_dims
    .group_segment_fixed_size: 0
    .kernarg_segment_align: 8
    .kernarg_segment_size: 272
    .language:       OpenCL C
    .language_version:
      - 2
      - 0
    .max_flat_workgroup_size: 1024
    .name:           _ZN2nv6k_snapEPKfPf
    .private_segment_fixed_size: 0
    .sgpr_count:     16
    .sgpr_spill_count: 0
    .symbol:         _ZN2nv6k_snapEPKfPf.kd
    .uniform_work_group_size: 1
    .uses_dynamic_stack: false
    .vgpr_count:     6
    .vgpr_spill_count: 0
    .wavefront_size: 64
  - .agpr_count:     0
    .args:
      - .offset:         0
        .size:           336
        .value_kind:     by_value
      - .offset:         336
        .size:           4
        .value_kind:     hidden_block_count_x
      - .offset:         340
        .size:           4
        .value_kind:     hidden_block_count_y
      - .offset:         344
        .size:           4
        .value_kind:     hidden_block_count_z
      - .offset:         348
        .size:           2
        .value_kind:     hidden_group_size_x
      - .offset:         350
        .size:           2
        .value_kind:     hidden_group_size_y
      - .offset:         352
        .size:           2
        .value_kind:     hidden_group_size_z
      - .offset:         354
        .size:           2
        .value_kind:     hidden_remainder_x
      - .offset:         356
        .size:           2
        .value_kind:     hidden_remainder_y
      - .offset:         358
        .size:           2
        .value_kind:     hidden_remainder_z
      - .offset:         376
        .size:           8
        .value_kind:     hidden_global_offset_x
      - .offset:         384
        .size:           8
        .value_kind:     hidden_global_offset_y
      - .offset:         392
        .size:           8
        .value_kind:     hidden_global_offset_z
      - .offset:         400
        .size:           2
        .value_kind:     hidden_grid_dims
      - .offset:         456
        .size:           4
        .value_kind:     hidden_dynamic_lds_size
    .group_segment_fixed_size: 0
    .kernarg_segment_align: 8
    .kernarg_segment_size: 592
    .language:       OpenCL C
    .language_version:
      - 2
      - 0
    .max_flat_workgroup_size: 512
    .name:           _ZN2mk8mega_fwdENS_6ParamsE
    .private_segment_fixed_size: 0
    .sgpr_count:     108
    .sgpr_spill_count: 453
    .symbol:         _ZN2mk8mega_fwdENS_6ParamsE.kd
    .uniform_work_group_size: 1
    .uses_dynamic_stack: false
    .vgpr_count:     256
    .vgpr_spill_count: 0
    .wavefront_size: 64
  - .agpr_count:     0
    .args:
      - .offset:         0
        .size:           1032
        .value_kind:     by_value
      - .address_space:  global
        .offset:         1032
        .size:           8
        .value_kind:     global_buffer
      - .offset:         1040
        .size:           4
        .value_kind:     hidden_block_count_x
      - .offset:         1044
        .size:           4
        .value_kind:     hidden_block_count_y
      - .offset:         1048
        .size:           4
        .value_kind:     hidden_block_count_z
      - .offset:         1052
        .size:           2
        .value_kind:     hidden_group_size_x
      - .offset:         1054
        .size:           2
        .value_kind:     hidden_group_size_y
      - .offset:         1056
        .size:           2
        .value_kind:     hidden_group_size_z
      - .offset:         1058
        .size:           2
        .value_kind:     hidden_remainder_x
      - .offset:         1060
        .size:           2
        .value_kind:     hidden_remainder_y
      - .offset:         1062
        .size:           2
        .value_kind:     hidden_remainder_z
      - .offset:         1080
        .size:           8
        .value_kind:     hidden_global_offset_x
      - .offset:         1088
        .size:           8
        .value_kind:     hidden_global_offset_y
      - .offset:         1096
        .size:           8
        .value_kind:     hidden_global_offset_z
      - .offset:         1104
        .size:           2
        .value_kind:     hidden_grid_dims
    .group_segment_fixed_size: 5120
    .kernarg_segment_align: 8
    .kernarg_segment_size: 1296
    .language:       OpenCL C
    .language_version:
      - 2
      - 0
    .max_flat_workgroup_size: 256
    .name:           _ZN3dbg5k_cmpENS_6ChkAllEPd
    .private_segment_fixed_size: 0
    .sgpr_count:     24
    .sgpr_spill_count: 0
    .symbol:         _ZN3dbg5k_cmpENS_6ChkAllEPd.kd
    .uniform_work_group_size: 1
    .uses_dynamic_stack: false
    .vgpr_count:     17
    .vgpr_spill_count: 0
    .wavefront_size: 64
  - .agpr_count:     0
    .args:
      - .address_space:  global
        .offset:         0
        .size:           8
        .value_kind:     global_buffer
      - .address_space:  global
        .offset:         8
        .size:           8
        .value_kind:     global_buffer
      - .offset:         16
        .size:           4
        .value_kind:     by_value
    .group_segment_fixed_size: 0
    .kernarg_segment_align: 8
    .kernarg_segment_size: 20
    .language:       OpenCL C
    .language_version:
      - 2
      - 0
    .max_flat_workgroup_size: 1024
    .name:           _ZN3dbg8k_encodeEPKdPii
    .private_segment_fixed_size: 0
    .sgpr_count:     46
    .sgpr_spill_count: 0
    .symbol:         _ZN3dbg8k_encodeEPKdPii.kd
    .uniform_work_group_size: 1
    .uses_dynamic_stack: false
    .vgpr_count:     30
    .vgpr_spill_count: 0
    .wavefront_size: 64
  - .agpr_count:     0
    .args:
      - .address_space:  global
        .offset:         0
        .size:           8
        .value_kind:     global_buffer
      - .address_space:  global
        .offset:         8
        .size:           8
        .value_kind:     global_buffer
      - .offset:         16
        .size:           8
        .value_kind:     by_value
      - .address_space:  global
        .offset:         24
        .size:           8
        .value_kind:     global_buffer
      - .offset:         32
        .size:           4
        .value_kind:     hidden_block_count_x
      - .offset:         36
        .size:           4
        .value_kind:     hidden_block_count_y
      - .offset:         40
        .size:           4
        .value_kind:     hidden_block_count_z
      - .offset:         44
        .size:           2
        .value_kind:     hidden_group_size_x
      - .offset:         46
        .size:           2
        .value_kind:     hidden_group_size_y
      - .offset:         48
        .size:           2
        .value_kind:     hidden_group_size_z
      - .offset:         50
        .size:           2
        .value_kind:     hidden_remainder_x
      - .offset:         52
        .size:           2
        .value_kind:     hidden_remainder_y
      - .offset:         54
        .size:           2
        .value_kind:     hidden_remainder_z
      - .offset:         72
        .size:           8
        .value_kind:     hidden_global_offset_x
      - .offset:         80
        .size:           8
        .value_kind:     hidden_global_offset_y
      - .offset:         88
        .size:           8
        .value_kind:     hidden_global_offset_z
      - .offset:         96
        .size:           2
        .value_kind:     hidden_grid_dims
    .group_segment_fixed_size: 0
    .kernarg_segment_align: 8
    .kernarg_segment_size: 288
    .language:       OpenCL C
    .language_version:
      - 2
      - 0
    .max_flat_workgroup_size: 1024
    .name:           _ZN3dbg7k_applyEPfPKfmPKi
    .private_segment_fixed_size: 0
    .sgpr_count:     23
    .sgpr_spill_count: 0
    .symbol:         _ZN3dbg7k_applyEPfPKfmPKi.kd
    .uniform_work_group_size: 1
    .uses_dynamic_stack: false
    .vgpr_count:     10
    .vgpr_spill_count: 0
    .wavefront_size: 64
